# A5 epilogue: second half-tile's gate loads issued together with the first half's
# baseline (speedup 1.0000x reference)
.LBB0_812:
	s_lshl_b32 s2, s2, 8
	v_mov_b32_e32 v128, v231
	v_mov_b32_e32 v129, v230
	s_add_i32 s2, s2, s37
	s_lshl_b32 s20, s3, 10
	v_add_u32_e32 v174, s2, v129
	s_lshl_b32 s2, s33, 8
	s_or_b32 s2, s2, s38
	v_ashrrev_i32_e32 v175, 31, v174
	v_lshl_add_u32 v172, v128, 3, s2
	v_lshlrev_b64 v[128:129], 14, v[174:175]
	s_ashr_i32 s21, s20, 31
	v_lshl_add_u64 v[128:129], s[8:9], 0, v[128:129]
	v_lshl_add_u64 v[128:129], v[128:129], 0, s[20:21]
	v_ashrrev_i32_e32 v173, 31, v172
	v_lshl_add_u64 v[128:129], v[128:129], 0, v[172:173]
	v_add_co_u32_e32 v130, vcc, 0x2000, v128
	s_cmp_lg_u32 s3, 0
	s_nop 0
	v_addc_co_u32_e32 v131, vcc, 0, v129, vcc
	global_load_dwordx2 v[200:201], v[130:131], off offset:1024
	s_mov_b64 s[98:99], 0x200000
	v_lshl_add_u64 v[236:237], v[130:131], 0, s[98:99]
	global_load_dwordx2 v[238:239], v[236:237], off offset:1024
	v_lshlrev_b64 v[130:131], 11, v[174:175]
	v_lshl_add_u64 v[198:199], s[4:5], 0, v[130:131]
	s_cselect_b64 s[22:23], -1, 0
	s_cmp_eq_u32 s3, 0
	v_lshl_add_u64 v[130:131], v[172:173], 1, v[198:199]
	s_cbranch_scc1 .LBB0_814
	global_load_dwordx4 v[158:161], v[130:131], off
	s_branch .LBB0_815

.LBB0_815:
	v_lshl_add_u64 v[128:129], v[128:129], 0, s[72:73]
	global_load_dwordx2 v[196:197], v[128:129], off offset:128
	v_lshl_add_u64 v[226:227], v[128:129], 0, s[98:99]
	global_load_dwordx2 v[240:241], v[226:227], off offset:128
	v_cndmask_b32_e64 v128, 0, 1, s[22:23]
	v_mov_b32_e32 v146, 0
	v_cmp_ne_u32_e64 s[2:3], 1, v128
	s_andn2_b64 vcc, exec, s[22:23]
	v_mov_b32_e32 v154, 0
	v_mov_b32_e32 v155, 0
	v_mov_b32_e32 v156, 0
	v_mov_b32_e32 v157, 0
	s_cbranch_vccnz .LBB0_817
	global_load_dwordx4 v[154:157], v[130:131], off offset:256
.LBB0_817:
	v_add_u32_e32 v130, 16, v174
	v_ashrrev_i32_e32 v131, 31, v130
	v_lshlrev_b64 v[128:129], 14, v[130:131]
	v_lshl_add_u64 v[128:129], s[8:9], 0, v[128:129]
	v_lshl_add_u64 v[128:129], v[128:129], 0, s[20:21]
	v_lshl_add_u64 v[128:129], v[128:129], 0, v[172:173]
	v_add_co_u32_e32 v132, vcc, 0x2000, v128
	v_lshlrev_b64 v[130:131], 11, v[130:131]
	s_nop 0
	v_addc_co_u32_e32 v133, vcc, 0, v129, vcc
	global_load_dwordx2 v[194:195], v[132:133], off offset:1024
	v_lshl_add_u64 v[236:237], v[132:133], 0, s[98:99]
	global_load_dwordx2 v[242:243], v[236:237], off offset:1024
	v_lshl_add_u64 v[192:193], s[4:5], 0, v[130:131]
	s_and_b64 vcc, exec, s[2:3]
	v_lshl_add_u64 v[130:131], v[172:173], 1, v[192:193]
	v_mov_b32_e32 v147, 0
	v_mov_b32_e32 v148, 0
	v_mov_b32_e32 v149, 0
	s_cbranch_vccnz .LBB0_819
	global_load_dwordx4 v[146:149], v[130:131], off
.LBB0_819:
	v_lshl_add_u64 v[128:129], v[128:129], 0, s[72:73]
	global_load_dwordx2 v[190:191], v[128:129], off offset:128
	v_lshl_add_u64 v[226:227], v[128:129], 0, s[98:99]
	global_load_dwordx2 v[244:245], v[226:227], off offset:128
	v_mov_b32_e32 v138, 0
	s_and_b64 vcc, exec, s[2:3]
	v_mov_b32_e32 v150, 0
	v_mov_b32_e32 v151, 0
	v_mov_b32_e32 v152, 0
	v_mov_b32_e32 v153, 0
	s_cbranch_vccnz .LBB0_821
	global_load_dwordx4 v[150:153], v[130:131], off offset:256
.LBB0_821:
	v_add_u32_e32 v130, 32, v174
	v_ashrrev_i32_e32 v131, 31, v130
	v_lshlrev_b64 v[128:129], 14, v[130:131]
	v_lshl_add_u64 v[128:129], s[8:9], 0, v[128:129]
	v_lshl_add_u64 v[128:129], v[128:129], 0, s[20:21]
	v_lshl_add_u64 v[128:129], v[128:129], 0, v[172:173]
	v_add_co_u32_e32 v132, vcc, 0x2000, v128
	v_lshlrev_b64 v[130:131], 11, v[130:131]
	s_nop 0
	v_addc_co_u32_e32 v133, vcc, 0, v129, vcc
	global_load_dwordx2 v[188:189], v[132:133], off offset:1024
	v_lshl_add_u64 v[236:237], v[132:133], 0, s[98:99]
	global_load_dwordx2 v[246:247], v[236:237], off offset:1024
	v_lshl_add_u64 v[186:187], s[4:5], 0, v[130:131]
	s_and_b64 vcc, exec, s[2:3]
	v_lshl_add_u64 v[132:133], v[172:173], 1, v[186:187]
	v_mov_b32_e32 v139, 0
	v_mov_b32_e32 v140, 0
	v_mov_b32_e32 v141, 0
	s_cbranch_vccnz .LBB0_823
	global_load_dwordx4 v[138:141], v[132:133], off
.LBB0_823:
	v_lshl_add_u64 v[128:129], v[128:129], 0, s[72:73]
	global_load_dwordx2 v[184:185], v[128:129], off offset:128
	v_lshl_add_u64 v[226:227], v[128:129], 0, s[98:99]
	global_load_dwordx2 v[250:251], v[226:227], off offset:128
	v_mov_b32_e32 v130, 0
	s_and_b64 vcc, exec, s[2:3]
	v_mov_b32_e32 v142, 0
	v_mov_b32_e32 v143, 0
	v_mov_b32_e32 v144, 0
	v_mov_b32_e32 v145, 0
	s_cbranch_vccnz .LBB0_825
	global_load_dwordx4 v[142:145], v[132:133], off offset:256
.LBB0_825:
	v_add_u32_e32 v132, 48, v174
	v_ashrrev_i32_e32 v133, 31, v132
	v_lshlrev_b64 v[128:129], 14, v[132:133]
	v_lshl_add_u64 v[128:129], s[8:9], 0, v[128:129]
	v_lshl_add_u64 v[128:129], v[128:129], 0, s[20:21]
	v_lshl_add_u64 v[128:129], v[128:129], 0, v[172:173]
	v_add_co_u32_e32 v134, vcc, 0x2000, v128
	v_lshlrev_b64 v[132:133], 11, v[132:133]
	s_nop 0
	v_addc_co_u32_e32 v135, vcc, 0, v129, vcc
	global_load_dwordx2 v[182:183], v[134:135], off offset:1024
	v_lshl_add_u64 v[236:237], v[134:135], 0, s[98:99]
	global_load_dwordx2 v[252:253], v[236:237], off offset:1024
	v_lshl_add_u64 v[180:181], s[4:5], 0, v[132:133]
	s_and_b64 vcc, exec, s[2:3]
	v_lshl_add_u64 v[202:203], v[172:173], 1, v[180:181]
	v_mov_b32_e32 v131, 0
	v_mov_b32_e32 v132, 0
	v_mov_b32_e32 v133, 0
	s_cbranch_vccnz .LBB0_827
	global_load_dwordx4 v[130:133], v[202:203], off
.LBB0_827:
	v_lshl_add_u64 v[128:129], v[128:129], 0, s[72:73]
	global_load_dwordx2 v[178:179], v[128:129], off offset:128
	v_lshl_add_u64 v[226:227], v[128:129], 0, s[98:99]
	global_load_dwordx2 v[234:235], v[226:227], off offset:128
	v_mov_b32_e32 v128, 0
	s_and_b64 vcc, exec, s[2:3]
	v_mov_b32_e32 v134, 0
	v_mov_b32_e32 v135, 0
	v_mov_b32_e32 v136, 0
	v_mov_b32_e32 v137, 0
	s_cbranch_vccnz .LBB0_829
	global_load_dwordx4 v[134:137], v[202:203], off offset:256
.LBB0_829:
	s_waitcnt vmcnt(0)
	v_cvt_f32_ubyte1_e32 v205, v200
	v_cvt_f32_ubyte0_e32 v204, v200
	v_lshlrev_b32_e32 v202, 16, v158
	v_and_b32_e32 v203, 0xffff0000, v158
	v_pk_mul_f32 v[204:205], v[204:205], s[80:81] op_sel_hi:[1,0]
	v_lshlrev_b32_e32 v158, 16, v159
	v_pk_fma_f32 v[124:125], v[124:125], v[204:205], v[202:203]
	v_cvt_f32_ubyte1_e32 v205, v201
	v_cvt_f32_ubyte0_e32 v204, v201
	v_lshlrev_b32_e32 v202, 16, v160
	v_and_b32_e32 v203, 0xffff0000, v160
	v_pk_mul_f32 v[204:205], v[204:205], s[80:81] op_sel_hi:[1,0]
	v_and_b32_e32 v159, 0xffff0000, v159
	v_pk_fma_f32 v[120:121], v[120:121], v[204:205], v[202:203]
	v_cvt_f32_ubyte3_e32 v203, v200
	v_cvt_f32_ubyte2_e32 v202, v200
	v_pk_mul_f32 v[202:203], v[202:203], s[80:81] op_sel_hi:[1,0]
	v_cvt_f32_ubyte2_e32 v160, v201
	v_pk_fma_f32 v[126:127], v[126:127], v[202:203], v[158:159]
	v_lshlrev_b32_e32 v158, 16, v161
	v_and_b32_e32 v159, 0xffff0000, v161
	v_cvt_f32_ubyte3_e32 v161, v201
	v_pk_mul_f32 v[160:161], v[160:161], s[80:81] op_sel_hi:[1,0]
	v_mov_b32_e32 v129, 0
	v_pk_fma_f32 v[158:159], v[122:123], v[160:161], v[158:159]
	v_cvt_pk_bf16_f32 v122, v124, v125
	v_cvt_pk_bf16_f32 v124, v120, v121
	v_lshlrev_b64 v[120:121], 1, v[172:173]
	v_cvt_pk_bf16_f32 v123, v126, v127
	v_cvt_pk_bf16_f32 v125, v158, v159
	v_lshl_add_u64 v[126:127], v[198:199], 0, v[120:121]
	global_store_dwordx4 v[126:127], v[122:125], off
	s_nop 1
	v_cvt_f32_ubyte1_e32 v125, v196
	v_cvt_f32_ubyte0_e32 v124, v196
	v_lshlrev_b32_e32 v122, 16, v154
	v_and_b32_e32 v123, 0xffff0000, v154
	v_pk_mul_f32 v[124:125], v[124:125], s[80:81] op_sel_hi:[1,0]
	s_nop 0
	v_pk_fma_f32 v[116:117], v[116:117], v[124:125], v[122:123]
	v_cvt_f32_ubyte1_e32 v125, v197
	v_cvt_f32_ubyte0_e32 v124, v197
	v_lshlrev_b32_e32 v122, 16, v156
	v_and_b32_e32 v123, 0xffff0000, v156
	v_pk_mul_f32 v[124:125], v[124:125], s[80:81] op_sel_hi:[1,0]
	s_nop 0
	v_pk_fma_f32 v[122:123], v[112:113], v[124:125], v[122:123]
	v_cvt_f32_ubyte3_e32 v125, v196
	v_cvt_f32_ubyte2_e32 v124, v196
	v_lshlrev_b32_e32 v112, 16, v155
	v_and_b32_e32 v113, 0xffff0000, v155
	v_pk_mul_f32 v[124:125], v[124:125], s[80:81] op_sel_hi:[1,0]
	s_nop 0
	v_pk_fma_f32 v[118:119], v[118:119], v[124:125], v[112:113]
	v_cvt_f32_ubyte3_e32 v125, v197
	v_cvt_f32_ubyte2_e32 v124, v197
	v_lshlrev_b32_e32 v112, 16, v157
	v_and_b32_e32 v113, 0xffff0000, v157
	v_pk_mul_f32 v[124:125], v[124:125], s[80:81] op_sel_hi:[1,0]
	s_nop 0
	v_pk_fma_f32 v[124:125], v[114:115], v[124:125], v[112:113]
	v_cvt_pk_bf16_f32 v112, v116, v117
	v_cvt_pk_bf16_f32 v113, v118, v119
	v_cvt_pk_bf16_f32 v114, v122, v123
	v_cvt_pk_bf16_f32 v115, v124, v125
	global_store_dwordx4 v[126:127], v[112:115], off offset:256
	s_nop 1
	v_cvt_f32_ubyte1_e32 v115, v194
	v_cvt_f32_ubyte0_e32 v114, v194
	v_lshlrev_b32_e32 v112, 16, v146
	v_and_b32_e32 v113, 0xffff0000, v146
	v_pk_mul_f32 v[114:115], v[114:115], s[80:81] op_sel_hi:[1,0]
	s_nop 0
	v_pk_fma_f32 v[108:109], v[108:109], v[114:115], v[112:113]
	v_cvt_f32_ubyte1_e32 v115, v195
	v_cvt_f32_ubyte0_e32 v114, v195
	v_lshlrev_b32_e32 v112, 16, v148
	v_and_b32_e32 v113, 0xffff0000, v148
	v_pk_mul_f32 v[114:115], v[114:115], s[80:81] op_sel_hi:[1,0]
	s_nop 0
	v_pk_fma_f32 v[112:113], v[104:105], v[114:115], v[112:113]
	v_cvt_f32_ubyte3_e32 v115, v194
	v_cvt_f32_ubyte2_e32 v114, v194
	v_lshlrev_b32_e32 v104, 16, v147
	v_and_b32_e32 v105, 0xffff0000, v147
	v_pk_mul_f32 v[114:115], v[114:115], s[80:81] op_sel_hi:[1,0]
	s_nop 0
	v_pk_fma_f32 v[110:111], v[110:111], v[114:115], v[104:105]
	v_cvt_f32_ubyte3_e32 v115, v195
	v_cvt_f32_ubyte2_e32 v114, v195
	v_lshlrev_b32_e32 v104, 16, v149
	v_and_b32_e32 v105, 0xffff0000, v149
	v_pk_mul_f32 v[114:115], v[114:115], s[80:81] op_sel_hi:[1,0]
	s_nop 0
	v_pk_fma_f32 v[114:115], v[106:107], v[114:115], v[104:105]
	v_cvt_pk_bf16_f32 v104, v108, v109
	v_cvt_pk_bf16_f32 v105, v110, v111
	v_cvt_pk_bf16_f32 v106, v112, v113
	v_cvt_pk_bf16_f32 v107, v114, v115
	v_lshl_add_u64 v[108:109], v[192:193], 0, v[120:121]
	global_store_dwordx4 v[108:109], v[104:107], off
	s_nop 1
	v_cvt_f32_ubyte1_e32 v107, v190
	v_cvt_f32_ubyte0_e32 v106, v190
	v_lshlrev_b32_e32 v104, 16, v150
	v_and_b32_e32 v105, 0xffff0000, v150
	v_pk_mul_f32 v[106:107], v[106:107], s[80:81] op_sel_hi:[1,0]
	s_nop 0
	v_pk_fma_f32 v[100:101], v[100:101], v[106:107], v[104:105]
	v_cvt_f32_ubyte1_e32 v107, v191
	v_cvt_f32_ubyte0_e32 v106, v191
	v_lshlrev_b32_e32 v104, 16, v152
	v_and_b32_e32 v105, 0xffff0000, v152
	v_pk_mul_f32 v[106:107], v[106:107], s[80:81] op_sel_hi:[1,0]
	s_nop 0
	v_pk_fma_f32 v[104:105], v[96:97], v[106:107], v[104:105]
	v_cvt_f32_ubyte3_e32 v107, v190
	v_cvt_f32_ubyte2_e32 v106, v190
	v_lshlrev_b32_e32 v96, 16, v151
	v_and_b32_e32 v97, 0xffff0000, v151
	v_pk_mul_f32 v[106:107], v[106:107], s[80:81] op_sel_hi:[1,0]
	s_nop 0
	v_pk_fma_f32 v[102:103], v[102:103], v[106:107], v[96:97]
	v_cvt_f32_ubyte3_e32 v107, v191
	v_cvt_f32_ubyte2_e32 v106, v191
	v_lshlrev_b32_e32 v96, 16, v153
	v_and_b32_e32 v97, 0xffff0000, v153
	v_pk_mul_f32 v[106:107], v[106:107], s[80:81] op_sel_hi:[1,0]
	s_nop 0
	v_pk_fma_f32 v[106:107], v[98:99], v[106:107], v[96:97]
	v_cvt_pk_bf16_f32 v96, v100, v101
	v_cvt_pk_bf16_f32 v97, v102, v103
	v_cvt_pk_bf16_f32 v98, v104, v105
	v_cvt_pk_bf16_f32 v99, v106, v107
	global_store_dwordx4 v[108:109], v[96:99], off offset:256
	s_nop 1
	v_cvt_f32_ubyte1_e32 v99, v188
	v_cvt_f32_ubyte0_e32 v98, v188
	v_lshlrev_b32_e32 v96, 16, v138
	v_and_b32_e32 v97, 0xffff0000, v138
	v_pk_mul_f32 v[98:99], v[98:99], s[80:81] op_sel_hi:[1,0]
	s_nop 0
	v_pk_fma_f32 v[92:93], v[92:93], v[98:99], v[96:97]
	v_cvt_f32_ubyte1_e32 v99, v189
	v_cvt_f32_ubyte0_e32 v98, v189
	v_lshlrev_b32_e32 v96, 16, v140
	v_and_b32_e32 v97, 0xffff0000, v140
	v_pk_mul_f32 v[98:99], v[98:99], s[80:81] op_sel_hi:[1,0]
	s_nop 0
	v_pk_fma_f32 v[96:97], v[88:89], v[98:99], v[96:97]
	v_cvt_f32_ubyte3_e32 v99, v188
	v_cvt_f32_ubyte2_e32 v98, v188
	v_lshlrev_b32_e32 v88, 16, v139
	v_and_b32_e32 v89, 0xffff0000, v139
	v_pk_mul_f32 v[98:99], v[98:99], s[80:81] op_sel_hi:[1,0]
	s_nop 0
	v_pk_fma_f32 v[94:95], v[94:95], v[98:99], v[88:89]
	v_cvt_f32_ubyte3_e32 v99, v189
	v_cvt_f32_ubyte2_e32 v98, v189
	v_lshlrev_b32_e32 v88, 16, v141
	v_and_b32_e32 v89, 0xffff0000, v141
	v_pk_mul_f32 v[98:99], v[98:99], s[80:81] op_sel_hi:[1,0]
	s_nop 0
	v_pk_fma_f32 v[98:99], v[90:91], v[98:99], v[88:89]
	v_cvt_pk_bf16_f32 v88, v92, v93
	v_cvt_pk_bf16_f32 v89, v94, v95
	v_cvt_pk_bf16_f32 v90, v96, v97
	v_cvt_pk_bf16_f32 v91, v98, v99
	v_lshl_add_u64 v[92:93], v[186:187], 0, v[120:121]
	global_store_dwordx4 v[92:93], v[88:91], off
	s_nop 1
	v_cvt_f32_ubyte1_e32 v91, v184
	v_cvt_f32_ubyte0_e32 v90, v184
	v_lshlrev_b32_e32 v88, 16, v142
	v_and_b32_e32 v89, 0xffff0000, v142
	v_pk_mul_f32 v[90:91], v[90:91], s[80:81] op_sel_hi:[1,0]
	s_nop 0
	v_pk_fma_f32 v[84:85], v[84:85], v[90:91], v[88:89]
	v_cvt_f32_ubyte1_e32 v91, v185
	v_cvt_f32_ubyte0_e32 v90, v185
	v_lshlrev_b32_e32 v88, 16, v144
	v_and_b32_e32 v89, 0xffff0000, v144
	v_pk_mul_f32 v[90:91], v[90:91], s[80:81] op_sel_hi:[1,0]
	s_nop 0
	v_pk_fma_f32 v[88:89], v[80:81], v[90:91], v[88:89]
	v_cvt_f32_ubyte3_e32 v91, v184
	v_cvt_f32_ubyte2_e32 v90, v184
	v_lshlrev_b32_e32 v80, 16, v143
	v_and_b32_e32 v81, 0xffff0000, v143
	v_pk_mul_f32 v[90:91], v[90:91], s[80:81] op_sel_hi:[1,0]
	s_nop 0
	v_pk_fma_f32 v[86:87], v[86:87], v[90:91], v[80:81]
	v_cvt_f32_ubyte3_e32 v91, v185
	v_cvt_f32_ubyte2_e32 v90, v185
	v_lshlrev_b32_e32 v80, 16, v145
	v_and_b32_e32 v81, 0xffff0000, v145
	v_pk_mul_f32 v[90:91], v[90:91], s[80:81] op_sel_hi:[1,0]
	s_nop 0
	v_pk_fma_f32 v[90:91], v[82:83], v[90:91], v[80:81]
	v_cvt_pk_bf16_f32 v80, v84, v85
	v_cvt_pk_bf16_f32 v81, v86, v87
	v_cvt_pk_bf16_f32 v82, v88, v89
	v_cvt_pk_bf16_f32 v83, v90, v91
	global_store_dwordx4 v[92:93], v[80:83], off offset:256
	s_nop 1
	v_cvt_f32_ubyte1_e32 v83, v182
	v_cvt_f32_ubyte0_e32 v82, v182
	v_lshlrev_b32_e32 v80, 16, v130
	v_and_b32_e32 v81, 0xffff0000, v130
	v_pk_mul_f32 v[82:83], v[82:83], s[80:81] op_sel_hi:[1,0]
	v_mov_b32_e32 v130, 0
	v_pk_fma_f32 v[76:77], v[76:77], v[82:83], v[80:81]
	v_cvt_f32_ubyte1_e32 v83, v183
	v_cvt_f32_ubyte0_e32 v82, v183
	v_lshlrev_b32_e32 v80, 16, v132
	v_and_b32_e32 v81, 0xffff0000, v132
	v_pk_mul_f32 v[82:83], v[82:83], s[80:81] op_sel_hi:[1,0]
	s_nop 0
	v_pk_fma_f32 v[80:81], v[72:73], v[82:83], v[80:81]
	v_cvt_f32_ubyte3_e32 v83, v182
	v_cvt_f32_ubyte2_e32 v82, v182
	v_lshlrev_b32_e32 v72, 16, v131
	v_and_b32_e32 v73, 0xffff0000, v131
	v_pk_mul_f32 v[82:83], v[82:83], s[80:81] op_sel_hi:[1,0]
	v_mov_b32_e32 v131, 0
	v_pk_fma_f32 v[78:79], v[78:79], v[82:83], v[72:73]
	v_cvt_f32_ubyte3_e32 v83, v183
	v_cvt_f32_ubyte2_e32 v82, v183
	v_lshlrev_b32_e32 v72, 16, v133
	v_and_b32_e32 v73, 0xffff0000, v133
	v_pk_mul_f32 v[82:83], v[82:83], s[80:81] op_sel_hi:[1,0]
	s_nop 0
	v_pk_fma_f32 v[82:83], v[74:75], v[82:83], v[72:73]
	v_cvt_pk_bf16_f32 v72, v76, v77
	v_cvt_pk_bf16_f32 v73, v78, v79
	v_cvt_pk_bf16_f32 v74, v80, v81
	v_cvt_pk_bf16_f32 v75, v82, v83
	v_lshl_add_u64 v[76:77], v[180:181], 0, v[120:121]
	global_store_dwordx4 v[76:77], v[72:75], off
	s_nop 1
	v_cvt_f32_ubyte1_e32 v75, v178
	v_cvt_f32_ubyte0_e32 v74, v178
	v_lshlrev_b32_e32 v72, 16, v134
	v_and_b32_e32 v73, 0xffff0000, v134
	v_pk_mul_f32 v[74:75], v[74:75], s[80:81] op_sel_hi:[1,0]
	s_nop 0
	v_pk_fma_f32 v[68:69], v[68:69], v[74:75], v[72:73]
	v_cvt_f32_ubyte1_e32 v75, v179
	v_cvt_f32_ubyte0_e32 v74, v179
	v_lshlrev_b32_e32 v72, 16, v136
	v_and_b32_e32 v73, 0xffff0000, v136
	v_pk_mul_f32 v[74:75], v[74:75], s[80:81] op_sel_hi:[1,0]
	s_nop 0
	v_pk_fma_f32 v[72:73], v[64:65], v[74:75], v[72:73]
	v_cvt_f32_ubyte3_e32 v75, v178
	v_cvt_f32_ubyte2_e32 v74, v178
	v_lshlrev_b32_e32 v64, 16, v135
	v_and_b32_e32 v65, 0xffff0000, v135
	v_pk_mul_f32 v[74:75], v[74:75], s[80:81] op_sel_hi:[1,0]
	s_nop 0
	v_pk_fma_f32 v[70:71], v[70:71], v[74:75], v[64:65]
	v_cvt_f32_ubyte3_e32 v75, v179
	v_cvt_f32_ubyte2_e32 v74, v179
	v_lshlrev_b32_e32 v64, 16, v137
	v_and_b32_e32 v65, 0xffff0000, v137
	v_pk_mul_f32 v[74:75], v[74:75], s[80:81] op_sel_hi:[1,0]
	s_nop 0
	v_pk_fma_f32 v[74:75], v[66:67], v[74:75], v[64:65]
	v_cvt_pk_bf16_f32 v64, v68, v69
	v_cvt_pk_bf16_f32 v65, v70, v71
	v_cvt_pk_bf16_f32 v66, v72, v73
	v_cvt_pk_bf16_f32 v67, v74, v75
	global_store_dwordx4 v[76:77], v[64:67], off offset:256
	s_nop 1
	v_add_u32_e32 v66, 0x80, v174
	v_ashrrev_i32_e32 v67, 31, v66
	v_lshlrev_b64 v[64:65], 14, v[66:67]
	v_lshl_add_u64 v[64:65], s[8:9], 0, v[64:65]
	v_lshl_add_u64 v[64:65], v[64:65], 0, s[20:21]
	v_lshl_add_u64 v[64:65], v[64:65], 0, v[172:173]
	v_add_co_u32_e32 v68, vcc, 0x2000, v64
	v_lshlrev_b64 v[66:67], 11, v[66:67]
	s_nop 0
	v_addc_co_u32_e32 v69, vcc, 0, v65, vcc
	v_mov_b32_e32 v114, v238
	v_mov_b32_e32 v115, v239
	v_lshl_add_u64 v[112:113], s[4:5], 0, v[66:67]
	s_and_b64 vcc, exec, s[2:3]
	v_lshl_add_u64 v[66:67], v[172:173], 1, v[112:113]
	s_cbranch_vccnz .LBB0_831
	global_load_dwordx4 v[128:131], v[66:67], off
.LBB0_831:
	v_lshl_add_u64 v[64:65], v[64:65], 0, s[72:73]
	v_mov_b32_e32 v110, v240
	v_mov_b32_e32 v111, v241
	v_mov_b32_e32 v80, 0
	s_and_b64 vcc, exec, s[2:3]
	v_mov_b32_e32 v88, 0
	v_mov_b32_e32 v89, 0
	v_mov_b32_e32 v90, 0
	v_mov_b32_e32 v91, 0
	s_cbranch_vccnz .LBB0_833
	global_load_dwordx4 v[88:91], v[66:67], off offset:256
.LBB0_833:
	v_add_u32_e32 v66, 0x90, v174
	v_ashrrev_i32_e32 v67, 31, v66
	v_lshlrev_b64 v[64:65], 14, v[66:67]
	v_lshl_add_u64 v[64:65], s[8:9], 0, v[64:65]
	v_lshl_add_u64 v[64:65], v[64:65], 0, s[20:21]
	v_lshl_add_u64 v[64:65], v[64:65], 0, v[172:173]
	v_add_co_u32_e32 v68, vcc, 0x2000, v64
	v_lshlrev_b64 v[66:67], 11, v[66:67]
	s_nop 0
	v_addc_co_u32_e32 v69, vcc, 0, v65, vcc
	v_mov_b32_e32 v108, v242
	v_mov_b32_e32 v109, v243
	v_lshl_add_u64 v[106:107], s[4:5], 0, v[66:67]
	s_and_b64 vcc, exec, s[2:3]
	v_lshl_add_u64 v[66:67], v[172:173], 1, v[106:107]
	v_mov_b32_e32 v81, 0
	v_mov_b32_e32 v82, 0
	v_mov_b32_e32 v83, 0
	s_cbranch_vccnz .LBB0_835
	global_load_dwordx4 v[80:83], v[66:67], off
.LBB0_835:
	v_lshl_add_u64 v[64:65], v[64:65], 0, s[72:73]
	v_mov_b32_e32 v104, v244
	v_mov_b32_e32 v105, v245
	v_mov_b32_e32 v72, 0
	s_and_b64 vcc, exec, s[2:3]
	v_mov_b32_e32 v84, 0
	v_mov_b32_e32 v85, 0
	v_mov_b32_e32 v86, 0
	v_mov_b32_e32 v87, 0
	s_cbranch_vccnz .LBB0_837
	global_load_dwordx4 v[84:87], v[66:67], off offset:256
.LBB0_837:
	v_add_u32_e32 v66, 0xa0, v174
	v_ashrrev_i32_e32 v67, 31, v66
	v_lshlrev_b64 v[64:65], 14, v[66:67]
	v_lshl_add_u64 v[64:65], s[8:9], 0, v[64:65]
	v_lshl_add_u64 v[64:65], v[64:65], 0, s[20:21]
	v_lshl_add_u64 v[64:65], v[64:65], 0, v[172:173]
	v_add_co_u32_e32 v68, vcc, 0x2000, v64
	v_lshlrev_b64 v[66:67], 11, v[66:67]
	s_nop 0
	v_addc_co_u32_e32 v69, vcc, 0, v65, vcc
	v_mov_b32_e32 v102, v246
	v_mov_b32_e32 v103, v247
	v_lshl_add_u64 v[100:101], s[4:5], 0, v[66:67]
	s_and_b64 vcc, exec, s[2:3]
	v_lshl_add_u64 v[66:67], v[172:173], 1, v[100:101]
	v_mov_b32_e32 v73, 0
	v_mov_b32_e32 v74, 0
	v_mov_b32_e32 v75, 0
	s_cbranch_vccnz .LBB0_839
	global_load_dwordx4 v[72:75], v[66:67], off
.LBB0_839:
	v_lshl_add_u64 v[64:65], v[64:65], 0, s[72:73]
	v_mov_b32_e32 v98, v250
	v_mov_b32_e32 v99, v251
	v_mov_b32_e32 v64, 0
	s_and_b64 vcc, exec, s[2:3]
	v_mov_b32_e32 v76, 0
	v_mov_b32_e32 v77, 0
	v_mov_b32_e32 v78, 0
	v_mov_b32_e32 v79, 0
	s_cbranch_vccnz .LBB0_841
	global_load_dwordx4 v[76:79], v[66:67], off offset:256
.LBB0_841:
	v_add_u32_e32 v66, 0xb0, v174
	v_ashrrev_i32_e32 v67, 31, v66
	v_lshlrev_b64 v[68:69], 14, v[66:67]
	v_lshl_add_u64 v[68:69], s[8:9], 0, v[68:69]
	v_lshl_add_u64 v[68:69], v[68:69], 0, s[20:21]
	v_lshl_add_u64 v[68:69], v[68:69], 0, v[172:173]
	v_add_co_u32_e32 v70, vcc, 0x2000, v68
	v_lshlrev_b64 v[66:67], 11, v[66:67]
	s_nop 0
	v_addc_co_u32_e32 v71, vcc, 0, v69, vcc
	v_mov_b32_e32 v96, v252
	v_mov_b32_e32 v97, v253
	v_lshl_add_u64 v[94:95], s[4:5], 0, v[66:67]
	s_and_b64 vcc, exec, s[2:3]
	v_lshl_add_u64 v[70:71], v[172:173], 1, v[94:95]
	v_mov_b32_e32 v65, 0
	v_mov_b32_e32 v66, 0
	v_mov_b32_e32 v67, 0
	s_cbranch_vccnz .LBB0_843
	global_load_dwordx4 v[64:67], v[70:71], off
.LBB0_843:
	v_lshl_add_u64 v[68:69], v[68:69], 0, s[72:73]
	v_mov_b32_e32 v92, v234
	v_mov_b32_e32 v93, v235
	s_and_b64 vcc, exec, s[2:3]
	s_cbranch_vccnz .LBB0_845
	global_load_dwordx4 v[68:71], v[70:71], off offset:256
	s_branch .LBB0_846
